# speedup vs baseline: 1.0129x; 1.0028x over previous
; #define WAIT_V(n) asm volatile("s_waitcnt vmcnt(" #n ")" ::: "memory")
; #define BAR __builtin_amdgcn_s_barrier()
;     ...
;     STAGE(SB(0, 0), Bt, bcol, 0); STAGE(SA(0, 0), A, brow, 0);
;     STAGE(SB(0, 1), Bt, bcol + HALF, 0); STAGE(SA(0, 1), A, brow + HALF, 0);
;     if (wr == 1) BAR;
;     WAIT_V(4); BAR;
;     STAGE(SB(1, 0), Bt, bcol, 1); STAGE(SA(1, 0), A, brow, 1); STAGE(SB(1, 1), Bt, bcol + HALF, 1);
;     WAIT_V(6); BAR;
;     for (int t = 0; t < nt - 2; t += 2) {
.LBB0_97:
	s_or_b32 s34, s48, 1
	s_mov_b32 s35, s49
	s_lshl_b64 s[42:43], s[34:35], 6
	s_add_u32 s34, s42, s6
	s_addc_u32 s35, s43, s4
	s_lshl_b64 s[34:35], s[34:35], 1
	s_add_u32 s44, s24, s34
	s_addc_u32 s45, s25, s35
	s_add_i32 s34, s15, 0x18000
	s_add_i32 s35, s15, 0x1a000
	s_add_u32 s4, s42, s5
	s_addc_u32 s5, s43, s7
	s_lshl_b64 s[4:5], s[4:5], 1
	v_mov_b32_e32 v141, v1
	s_waitcnt vmcnt(4)
	s_barrier
	s_mov_b32 m0, s34
	v_lshl_add_u64 v[4:5], s[44:45], 0, v[0:1]
	s_add_u32 s4, s22, s4
	global_load_lds_dwordx4 v[4:5], off
	v_lshl_add_u64 v[4:5], s[44:45], 0, v[140:141]
	s_mov_b32 m0, s35
	s_addc_u32 s5, s23, s5
	s_add_i32 s37, s15, 0x8000
	global_load_lds_dwordx4 v[4:5], off
	s_mov_b32 m0, s37
	v_lshl_add_u64 v[4:5], s[4:5], 0, v[0:1]
	s_waitcnt lgkmcnt(0)
	s_add_i32 s38, s15, 0xa000
	global_load_lds_dwordx4 v[4:5], off
	v_lshl_add_u64 v[4:5], s[4:5], 0, v[140:141]
	s_add_u32 s4, s42, s39
	s_addc_u32 s5, s43, s40
	s_lshl_b64 s[4:5], s[4:5], 1
	s_add_u32 s4, s24, s4
	s_mov_b32 m0, s38
	s_addc_u32 s5, s25, s5
	s_add_i32 s41, s15, 0x1c000
	global_load_lds_dwordx4 v[4:5], off
	s_mov_b32 m0, s41
	v_lshl_add_u64 v[4:5], s[4:5], 0, v[0:1]
	s_add_i32 s42, s15, 0x1e000
	global_load_lds_dwordx4 v[4:5], off
	v_lshl_add_u64 v[4:5], s[4:5], 0, v[140:141]
	s_mov_b32 m0, s42
	v_and_b32_e32 v3, 15, v2
	global_load_lds_dwordx4 v[4:5], off
	v_and_b32_e32 v6, 48, v2
	v_lshlrev_b32_e32 v2, 2, v2
	v_lshlrev_b32_e32 v4, 6, v3
	v_and_b32_e32 v2, 32, v2
	v_bitop3_b32 v142, v4, v2, v6 bitop3:0x36
	v_or_b32_e32 v2, s33, v3
	v_lshlrev_b32_e32 v4, 6, v2
	v_lshlrev_b32_e32 v2, 2, v2
	v_and_b32_e32 v4, 0x3c0, v4
	v_and_b32_e32 v2, 32, v2
	v_readlane_b32 s4, v245, 36
	s_add_i32 s43, s14, -2
	s_mul_i32 s40, s29, 0x2c00
	v_bitop3_b32 v4, v4, v2, v6 bitop3:0x36
	v_or_b32_e32 v2, s4, v3
	s_mul_hi_i32 s39, s29, 0x2c00
	s_add_u32 s55, s22, s40
	v_lshlrev_b32_e32 v5, 6, v2
	v_lshlrev_b32_e32 v2, 2, v2
	s_addc_u32 s57, s23, s39
	v_and_b32_e32 v5, 0x3c0, v5
	v_and_b32_e32 v2, 32, v2
	v_readlane_b32 s4, v245, 37
	s_ashr_i32 s7, s6, 31
	v_bitop3_b32 v5, v5, v2, v6 bitop3:0x36
	v_or_b32_e32 v2, s4, v3
	s_lshl_b64 s[4:5], s[48:49], 7
	s_lshl_b64 s[6:7], s[6:7], 1
	s_add_u32 s6, s24, s6
	v_lshlrev_b32_e32 v7, 6, v2
	v_lshlrev_b32_e32 v2, 2, v2
	s_addc_u32 s7, s25, s7
	s_mul_i32 s44, s20, 0x2c00
	v_and_b32_e32 v7, 0x3c0, v7
	v_and_b32_e32 v2, 32, v2
	s_mul_hi_i32 s45, s20, 0x2c00
	s_add_u32 s44, s22, s44
	v_bitop3_b32 v7, v7, v2, v6 bitop3:0x36
	v_or_b32_e32 v2, s85, v3
	s_addc_u32 s45, s23, s45
	s_mul_i32 s50, s10, 0x2c00
	v_readlane_b32 s59, v244, 19
	v_lshlrev_b32_e32 v3, 6, v2
	v_lshlrev_b32_e32 v2, 2, v2
	s_mul_hi_i32 s51, s10, 0x2c00
	s_add_u32 s50, s24, s50
	v_add_u32_e32 v133, s59, v4
	v_readlane_b32 s59, v244, 20
	s_waitcnt vmcnt(6)
	v_and_b32_e32 v3, 0x3c0, v3
	v_and_b32_e32 v2, 32, v2
	s_addc_u32 s51, s25, s51
	v_add_u32_e32 v134, s59, v5
	v_readlane_b32 s59, v244, 21
	v_bitop3_b32 v3, v3, v2, v6 bitop3:0x36
	s_add_u32 s55, s55, 0x80
	v_mov_b32_e32 v2, 0
	v_add_u32_e32 v137, s59, v7
	v_readlane_b32 s59, v244, 22
	s_addc_u32 s57, s57, 0
	s_mov_b32 s58, 0
	v_add_u32_e32 v139, s59, v3
	v_mov_b32_e32 v3, v2
	v_mov_b32_e32 v4, v2
	v_mov_b32_e32 v5, v2
	v_mov_b32_e32 v6, v2
	v_mov_b32_e32 v7, v2
	v_mov_b32_e32 v8, v2
	v_mov_b32_e32 v9, v2
	v_mov_b32_e32 v10, v2
	v_mov_b32_e32 v11, v2
	v_mov_b32_e32 v12, v2
	v_mov_b32_e32 v13, v2
	v_mov_b32_e32 v14, v2
	v_mov_b32_e32 v15, v2
	v_mov_b32_e32 v16, v2
	v_mov_b32_e32 v17, v2
	v_mov_b32_e32 v18, v2
	v_mov_b32_e32 v19, v2
	v_mov_b32_e32 v20, v2
	v_mov_b32_e32 v21, v2
	v_mov_b32_e32 v22, v2
	v_mov_b32_e32 v23, v2
	v_mov_b32_e32 v24, v2
	v_mov_b32_e32 v25, v2
	v_mov_b32_e32 v26, v2
	v_mov_b32_e32 v27, v2
	v_mov_b32_e32 v28, v2
	v_mov_b32_e32 v29, v2
	v_mov_b32_e32 v30, v2
	v_mov_b32_e32 v31, v2
	v_mov_b32_e32 v32, v2
	v_mov_b32_e32 v33, v2
	v_mov_b32_e32 v34, v2
	v_mov_b32_e32 v35, v2
	v_mov_b32_e32 v36, v2
	v_mov_b32_e32 v37, v2
	v_mov_b32_e32 v38, v2
	v_mov_b32_e32 v39, v2
	v_mov_b32_e32 v40, v2
	v_mov_b32_e32 v41, v2
	v_mov_b32_e32 v42, v2
	v_mov_b32_e32 v43, v2
	v_mov_b32_e32 v44, v2
	v_mov_b32_e32 v45, v2
	v_mov_b32_e32 v46, v2
	v_mov_b32_e32 v47, v2
	v_mov_b32_e32 v48, v2
	v_mov_b32_e32 v49, v2
	v_mov_b32_e32 v50, v2
	v_mov_b32_e32 v51, v2
	v_mov_b32_e32 v52, v2
	v_mov_b32_e32 v53, v2
	v_mov_b32_e32 v54, v2
	v_mov_b32_e32 v55, v2
	v_mov_b32_e32 v56, v2
	v_mov_b32_e32 v57, v2
	v_mov_b32_e32 v58, v2
	v_mov_b32_e32 v59, v2
	v_mov_b32_e32 v60, v2
	v_mov_b32_e32 v61, v2
	v_mov_b32_e32 v62, v2
	v_mov_b32_e32 v63, v2
	v_mov_b32_e32 v64, v2
	v_mov_b32_e32 v65, v2
	v_mov_b32_e32 v66, v2
	v_mov_b32_e32 v67, v2
	v_mov_b32_e32 v68, v2
	v_mov_b32_e32 v69, v2
	v_mov_b32_e32 v70, v2
	v_mov_b32_e32 v71, v2
	v_mov_b32_e32 v72, v2
	v_mov_b32_e32 v73, v2
	v_mov_b32_e32 v74, v2
	v_mov_b32_e32 v75, v2
	v_mov_b32_e32 v76, v2
	v_mov_b32_e32 v77, v2
	v_mov_b32_e32 v78, v2
	v_mov_b32_e32 v79, v2
	v_mov_b32_e32 v80, v2
	v_mov_b32_e32 v81, v2
	v_mov_b32_e32 v82, v2
	v_mov_b32_e32 v83, v2
	v_mov_b32_e32 v84, v2
	v_mov_b32_e32 v85, v2
	v_mov_b32_e32 v86, v2
	v_mov_b32_e32 v87, v2
	v_mov_b32_e32 v88, v2
	v_mov_b32_e32 v89, v2
	v_mov_b32_e32 v90, v2
	v_mov_b32_e32 v91, v2
	v_mov_b32_e32 v92, v2
	v_mov_b32_e32 v93, v2
	v_mov_b32_e32 v94, v2
	v_mov_b32_e32 v95, v2
	v_mov_b32_e32 v96, v2
	v_mov_b32_e32 v97, v2
	v_mov_b32_e32 v98, v2
	v_mov_b32_e32 v99, v2
	v_mov_b32_e32 v100, v2
	v_mov_b32_e32 v101, v2
	v_mov_b32_e32 v102, v2
	v_mov_b32_e32 v103, v2
	v_mov_b32_e32 v104, v2
	v_mov_b32_e32 v105, v2
	v_mov_b32_e32 v106, v2
	v_mov_b32_e32 v107, v2
	v_mov_b32_e32 v108, v2
	v_mov_b32_e32 v109, v2
	v_mov_b32_e32 v110, v2
	v_mov_b32_e32 v111, v2
	v_mov_b32_e32 v112, v2
	v_mov_b32_e32 v113, v2
	v_mov_b32_e32 v114, v2
	v_mov_b32_e32 v115, v2
	v_mov_b32_e32 v116, v2
	v_mov_b32_e32 v117, v2
	v_mov_b32_e32 v118, v2
	v_mov_b32_e32 v119, v2
	v_mov_b32_e32 v120, v2
	v_mov_b32_e32 v121, v2
	v_mov_b32_e32 v122, v2
	v_mov_b32_e32 v123, v2
	v_mov_b32_e32 v124, v2
	v_mov_b32_e32 v125, v2
	v_mov_b32_e32 v126, v2
	v_mov_b32_e32 v127, v2
	v_mov_b32_e32 v128, v2
	v_mov_b32_e32 v129, v2
	v_readlane_b32 vcc_lo, v245, 30
	s_nop 0
	s_cmpk_lt_u32 vcc_lo, 0x1000
	s_cbranch_scc1 .Lgp_98

; #define WAIT_V(n) asm volatile("s_waitcnt vmcnt(" #n ")" ::: "memory")
; #define BAR __builtin_amdgcn_s_barrier()
;     ...
;     STAGE(SB(0, 0), Bt, bcol, 0); STAGE(SA(0, 0), A, brow, 0);
;     STAGE(SB(0, 1), Bt, bcol + HALF, 0); STAGE(SA(0, 1), A, brow + HALF, 0);
;     if (wr == 1) BAR;
;     WAIT_V(4); BAR;
;     STAGE(SB(1, 0), Bt, bcol, 1); STAGE(SA(1, 0), A, brow, 1); STAGE(SB(1, 1), Bt, bcol + HALF, 1);
;     WAIT_V(6); BAR;
;     for (int t = 0; t < nt - 2; t += 2) {
.LBB0_154:
	s_add_u32 s34, s12, 0x80
	s_addc_u32 s35, s13, 0
	s_add_i32 s12, s24, 0x18000
	v_mov_b32_e32 v141, v1
	s_waitcnt vmcnt(4)
	s_barrier
	s_mov_b32 m0, s12
	v_lshl_add_u64 v[4:5], s[34:35], 0, v[0:1]
	s_add_i32 s13, s24, 0x1a000
	global_load_lds_dwordx4 v[4:5], off
	v_lshl_add_u64 v[4:5], s[34:35], 0, v[140:141]
	s_add_u32 s34, s14, 0x80
	s_mov_b32 m0, s13
	s_addc_u32 s35, s15, 0
	s_add_i32 s14, s24, 0x8000
	global_load_lds_dwordx4 v[4:5], off
	s_mov_b32 m0, s14
	v_lshl_add_u64 v[4:5], s[34:35], 0, v[0:1]
	s_add_i32 s15, s24, 0xa000
	global_load_lds_dwordx4 v[4:5], off
	v_lshl_add_u64 v[4:5], s[34:35], 0, v[140:141]
	s_add_u32 s34, s16, 0x80
	s_mov_b32 m0, s15
	s_addc_u32 s35, s17, 0
	s_add_i32 s16, s24, 0x1c000
	global_load_lds_dwordx4 v[4:5], off
	s_mov_b32 m0, s16
	v_lshl_add_u64 v[4:5], s[34:35], 0, v[0:1]
	s_add_i32 s17, s24, 0x1e000
	global_load_lds_dwordx4 v[4:5], off
	v_lshl_add_u64 v[4:5], s[34:35], 0, v[140:141]
	s_mov_b32 m0, s17
	v_and_b32_e32 v3, 15, v2
	global_load_lds_dwordx4 v[4:5], off
	v_and_b32_e32 v6, 48, v2
	v_lshlrev_b32_e32 v2, 2, v2
	v_lshlrev_b32_e32 v4, 6, v3
	v_and_b32_e32 v2, 32, v2
	v_bitop3_b32 v142, v4, v2, v6 bitop3:0x36
	v_or_b32_e32 v2, s33, v3
	v_lshlrev_b32_e32 v4, 6, v2
	v_lshlrev_b32_e32 v2, 2, v2
	v_and_b32_e32 v4, 0x3c0, v4
	v_and_b32_e32 v2, 32, v2
	v_readlane_b32 s34, v245, 36
	v_bitop3_b32 v4, v4, v2, v6 bitop3:0x36
	s_lshl_b32 s30, s30, 11
	v_or_b32_e32 v2, s34, v3
	v_lshlrev_b32_e32 v5, 6, v2
	v_lshlrev_b32_e32 v2, 2, v2
	v_and_b32_e32 v5, 0x3c0, v5
	v_and_b32_e32 v2, 32, v2
	v_readlane_b32 s34, v245, 37
	v_bitop3_b32 v5, v5, v2, v6 bitop3:0x36
	s_lshl_b32 s31, s31, 8
	v_or_b32_e32 v2, s34, v3
	v_lshlrev_b32_e32 v7, 6, v2
	v_lshlrev_b32_e32 v2, 2, v2
	s_add_i32 s30, s30, s31
	v_and_b32_e32 v7, 0x3c0, v7
	v_and_b32_e32 v2, 32, v2
	s_ashr_i32 s31, s30, 31
	v_bitop3_b32 v7, v7, v2, v6 bitop3:0x36
	v_or_b32_e32 v2, s85, v3
	s_lshl_b64 s[30:31], s[30:31], 12
	s_waitcnt lgkmcnt(0)
	v_readlane_b32 s38, v244, 19
	v_lshlrev_b32_e32 v3, 6, v2
	v_lshlrev_b32_e32 v2, 2, v2
	s_add_u32 s30, s74, s30
	v_add_u32_e32 v133, s38, v4
	v_readlane_b32 s38, v244, 20
	s_waitcnt vmcnt(6)
	v_and_b32_e32 v3, 0x3c0, v3
	v_and_b32_e32 v2, 32, v2
	s_addc_u32 s31, s75, s31
	v_add_u32_e32 v134, s38, v5
	v_readlane_b32 s38, v244, 21
	v_bitop3_b32 v3, v3, v2, v6 bitop3:0x36
	s_add_u32 s34, s18, s10
	v_mov_b32_e32 v2, 0
	v_add_u32_e32 v137, s38, v7
	v_readlane_b32 s38, v244, 22
	s_addc_u32 s35, s19, s11
	s_mov_b32 s37, -2
	s_mov_b64 s[10:11], 0
	v_add_u32_e32 v139, s38, v3
	v_mov_b32_e32 v3, v2
	v_mov_b32_e32 v4, v2
	v_mov_b32_e32 v5, v2
	v_mov_b32_e32 v6, v2
	v_mov_b32_e32 v7, v2
	v_mov_b32_e32 v8, v2
	v_mov_b32_e32 v9, v2
	v_mov_b32_e32 v10, v2
	v_mov_b32_e32 v11, v2
	v_mov_b32_e32 v12, v2
	v_mov_b32_e32 v13, v2
	v_mov_b32_e32 v14, v2
	v_mov_b32_e32 v15, v2
	v_mov_b32_e32 v16, v2
	v_mov_b32_e32 v17, v2
	v_mov_b32_e32 v18, v2
	v_mov_b32_e32 v19, v2
	v_mov_b32_e32 v20, v2
	v_mov_b32_e32 v21, v2
	v_mov_b32_e32 v22, v2
	v_mov_b32_e32 v23, v2
	v_mov_b32_e32 v24, v2
	v_mov_b32_e32 v25, v2
	v_mov_b32_e32 v26, v2
	v_mov_b32_e32 v27, v2
	v_mov_b32_e32 v28, v2
	v_mov_b32_e32 v29, v2
	v_mov_b32_e32 v30, v2
	v_mov_b32_e32 v31, v2
	v_mov_b32_e32 v32, v2
	v_mov_b32_e32 v33, v2
	v_mov_b32_e32 v34, v2
	v_mov_b32_e32 v35, v2
	v_mov_b32_e32 v36, v2
	v_mov_b32_e32 v37, v2
	v_mov_b32_e32 v38, v2
	v_mov_b32_e32 v39, v2
	v_mov_b32_e32 v40, v2
	v_mov_b32_e32 v41, v2
	v_mov_b32_e32 v42, v2
	v_mov_b32_e32 v43, v2
	v_mov_b32_e32 v44, v2
	v_mov_b32_e32 v45, v2
	v_mov_b32_e32 v46, v2
	v_mov_b32_e32 v47, v2
	v_mov_b32_e32 v48, v2
	v_mov_b32_e32 v49, v2
	v_mov_b32_e32 v50, v2
	v_mov_b32_e32 v51, v2
	v_mov_b32_e32 v52, v2
	v_mov_b32_e32 v53, v2
	v_mov_b32_e32 v54, v2
	v_mov_b32_e32 v55, v2
	v_mov_b32_e32 v56, v2
	v_mov_b32_e32 v57, v2
	v_mov_b32_e32 v58, v2
	v_mov_b32_e32 v59, v2
	v_mov_b32_e32 v60, v2
	v_mov_b32_e32 v61, v2
	v_mov_b32_e32 v62, v2
	v_mov_b32_e32 v63, v2
	v_mov_b32_e32 v64, v2
	v_mov_b32_e32 v65, v2
	v_mov_b32_e32 v66, v2
	v_mov_b32_e32 v67, v2
	v_mov_b32_e32 v68, v2
	v_mov_b32_e32 v69, v2
	v_mov_b32_e32 v70, v2
	v_mov_b32_e32 v71, v2
	v_mov_b32_e32 v72, v2
	v_mov_b32_e32 v73, v2
	v_mov_b32_e32 v74, v2
	v_mov_b32_e32 v75, v2
	v_mov_b32_e32 v76, v2
	v_mov_b32_e32 v77, v2
	v_mov_b32_e32 v78, v2
	v_mov_b32_e32 v79, v2
	v_mov_b32_e32 v80, v2
	v_mov_b32_e32 v81, v2
	v_mov_b32_e32 v82, v2
	v_mov_b32_e32 v83, v2
	v_mov_b32_e32 v84, v2
	v_mov_b32_e32 v85, v2
	v_mov_b32_e32 v86, v2
	v_mov_b32_e32 v87, v2
	v_mov_b32_e32 v88, v2
	v_mov_b32_e32 v89, v2
	v_mov_b32_e32 v90, v2
	v_mov_b32_e32 v91, v2
	v_mov_b32_e32 v92, v2
	v_mov_b32_e32 v93, v2
	v_mov_b32_e32 v94, v2
	v_mov_b32_e32 v95, v2
	v_mov_b32_e32 v96, v2
	v_mov_b32_e32 v97, v2
	v_mov_b32_e32 v98, v2
	v_mov_b32_e32 v99, v2
	v_mov_b32_e32 v100, v2
	v_mov_b32_e32 v101, v2
	v_mov_b32_e32 v102, v2
	v_mov_b32_e32 v103, v2
	v_mov_b32_e32 v104, v2
	v_mov_b32_e32 v105, v2
	v_mov_b32_e32 v106, v2
	v_mov_b32_e32 v107, v2
	v_mov_b32_e32 v108, v2
	v_mov_b32_e32 v109, v2
	v_mov_b32_e32 v110, v2
	v_mov_b32_e32 v111, v2
	v_mov_b32_e32 v112, v2
	v_mov_b32_e32 v113, v2
	v_mov_b32_e32 v114, v2
	v_mov_b32_e32 v115, v2
	v_mov_b32_e32 v116, v2
	v_mov_b32_e32 v117, v2
	v_mov_b32_e32 v118, v2
	v_mov_b32_e32 v119, v2
	v_mov_b32_e32 v120, v2
	v_mov_b32_e32 v121, v2
	v_mov_b32_e32 v122, v2
	v_mov_b32_e32 v123, v2
	v_mov_b32_e32 v124, v2
	v_mov_b32_e32 v125, v2
	v_mov_b32_e32 v126, v2
	v_mov_b32_e32 v127, v2
	v_mov_b32_e32 v128, v2
	v_mov_b32_e32 v129, v2
	v_readlane_b32 vcc_lo, v245, 30
	s_nop 0
	s_cmpk_lt_u32 vcc_lo, 0x1000
	s_cbranch_scc1 .Lgp_155

; #define WAIT_V(n) asm volatile("s_waitcnt vmcnt(" #n ")" ::: "memory")
; #define BAR __builtin_amdgcn_s_barrier()
;     ...
;     STAGE(SB(0, 0), Bt, bcol, 0); STAGE(SA(0, 0), A, brow, 0);
;     STAGE(SB(0, 1), Bt, bcol + HALF, 0); STAGE(SA(0, 1), A, brow + HALF, 0);
;     if (wr == 1) BAR;
;     WAIT_V(4); BAR;
;     STAGE(SB(1, 0), Bt, bcol, 1); STAGE(SA(1, 0), A, brow, 1); STAGE(SB(1, 1), Bt, bcol + HALF, 1);
;     WAIT_V(6); BAR;
;     for (int t = 0; t < nt - 2; t += 2) {
.LBB0_201:
	s_or_b32 s40, s48, 1
	s_mov_b32 s41, s49
	s_lshl_b64 s[44:45], s[40:41], 6
	s_add_u32 s4, s44, s4
	s_addc_u32 s5, s45, s5
	s_lshl_b64 s[4:5], s[4:5], 1
	s_add_u32 s4, s22, s4
	s_addc_u32 s5, s23, s5
	s_add_i32 s39, s21, 0x18000
	v_mov_b32_e32 v141, v1
	s_waitcnt vmcnt(4)
	s_barrier
	s_mov_b32 m0, s39
	v_lshl_add_u64 v[4:5], s[4:5], 0, v[0:1]
	s_add_i32 s40, s21, 0x1a000
	global_load_lds_dwordx4 v[4:5], off
	v_lshl_add_u64 v[4:5], s[4:5], 0, v[140:141]
	s_add_u32 s4, s44, s16
	s_addc_u32 s5, s45, s17
	s_lshl_b64 s[4:5], s[4:5], 1
	s_add_u32 s4, s74, s4
	s_mov_b32 m0, s40
	s_addc_u32 s5, s75, s5
	s_add_i32 s41, s21, 0x8000
	global_load_lds_dwordx4 v[4:5], off
	s_mov_b32 m0, s41
	v_lshl_add_u64 v[4:5], s[4:5], 0, v[0:1]
	s_add_i32 s42, s21, 0xa000
	global_load_lds_dwordx4 v[4:5], off
	v_lshl_add_u64 v[4:5], s[4:5], 0, v[140:141]
	s_add_u32 s4, s44, s18
	s_addc_u32 s5, s45, s19
	s_lshl_b64 s[4:5], s[4:5], 1
	s_add_u32 s4, s22, s4
	s_mov_b32 m0, s42
	s_addc_u32 s5, s23, s5
	s_add_i32 s18, s21, 0x1c000
	global_load_lds_dwordx4 v[4:5], off
	s_mov_b32 m0, s18
	v_lshl_add_u64 v[4:5], s[4:5], 0, v[0:1]
	s_add_i32 s19, s21, 0x1e000
	global_load_lds_dwordx4 v[4:5], off
	v_lshl_add_u64 v[4:5], s[4:5], 0, v[140:141]
	s_mov_b32 m0, s19
	v_and_b32_e32 v3, 15, v2
	global_load_lds_dwordx4 v[4:5], off
	v_and_b32_e32 v6, 48, v2
	v_lshlrev_b32_e32 v2, 2, v2
	v_lshlrev_b32_e32 v4, 6, v3
	v_and_b32_e32 v2, 32, v2
	v_bitop3_b32 v142, v4, v2, v6 bitop3:0x36
	v_or_b32_e32 v2, s33, v3
	v_lshlrev_b32_e32 v4, 6, v2
	v_lshlrev_b32_e32 v2, 2, v2
	s_lshl_b64 s[4:5], s[10:11], 12
	v_and_b32_e32 v4, 0x3c0, v4
	v_and_b32_e32 v2, 32, v2
	v_readlane_b32 s11, v245, 36
	s_add_i32 s43, s20, -2
	v_bitop3_b32 v4, v4, v2, v6 bitop3:0x36
	v_or_b32_e32 v2, s11, v3
	s_add_u32 s55, s74, s4
	v_lshlrev_b32_e32 v5, 6, v2
	v_lshlrev_b32_e32 v2, 2, v2
	s_addc_u32 s57, s75, s5
	v_and_b32_e32 v5, 0x3c0, v5
	v_and_b32_e32 v2, 32, v2
	v_readlane_b32 s11, v245, 37
	s_lshl_b64 s[16:17], s[48:49], 7
	s_lshl_b64 s[44:45], s[14:15], 12
	v_bitop3_b32 v5, v5, v2, v6 bitop3:0x36
	v_or_b32_e32 v2, s11, v3
	s_add_u32 s11, s22, s44
	s_addc_u32 s44, s23, s45
	s_lshl_b64 s[50:51], s[12:13], 12
	s_add_u32 s13, s74, s50
	v_lshlrev_b32_e32 v7, 6, v2
	v_lshlrev_b32_e32 v2, 2, v2
	s_addc_u32 s45, s75, s51
	v_and_b32_e32 v7, 0x3c0, v7
	v_and_b32_e32 v2, 32, v2
	s_add_u32 s50, s55, 0x80
	v_bitop3_b32 v7, v7, v2, v6 bitop3:0x36
	v_or_b32_e32 v2, s85, v3
	s_addc_u32 s51, s57, 0
	v_readlane_b32 s57, v244, 19
	v_lshlrev_b32_e32 v3, 6, v2
	v_lshlrev_b32_e32 v2, 2, v2
	v_add_u32_e32 v133, s57, v4
	v_readlane_b32 s57, v244, 20
	s_waitcnt vmcnt(6)
	v_and_b32_e32 v3, 0x3c0, v3
	v_and_b32_e32 v2, 32, v2
	v_add_u32_e32 v134, s57, v5
	v_readlane_b32 s57, v244, 21
	v_bitop3_b32 v3, v3, v2, v6 bitop3:0x36
	v_mov_b32_e32 v2, 0
	v_add_u32_e32 v137, s57, v7
	v_readlane_b32 s57, v244, 22
	s_mov_b32 s55, 0
	v_mov_b32_e32 v4, v2
	v_add_u32_e32 v139, s57, v3
	v_mov_b32_e32 v3, v2
	v_mov_b32_e32 v5, v2
	v_mov_b32_e32 v6, v2
	v_mov_b32_e32 v7, v2
	v_mov_b32_e32 v8, v2
	v_mov_b32_e32 v9, v2
	v_mov_b32_e32 v10, v2
	v_mov_b32_e32 v11, v2
	v_mov_b32_e32 v12, v2
	v_mov_b32_e32 v13, v2
	v_mov_b32_e32 v14, v2
	v_mov_b32_e32 v15, v2
	v_mov_b32_e32 v16, v2
	v_mov_b32_e32 v17, v2
	v_mov_b32_e32 v18, v2
	v_mov_b32_e32 v19, v2
	v_mov_b32_e32 v20, v2
	v_mov_b32_e32 v21, v2
	v_mov_b32_e32 v22, v2
	v_mov_b32_e32 v23, v2
	v_mov_b32_e32 v24, v2
	v_mov_b32_e32 v25, v2
	v_mov_b32_e32 v26, v2
	v_mov_b32_e32 v27, v2
	v_mov_b32_e32 v28, v2
	v_mov_b32_e32 v29, v2
	v_mov_b32_e32 v30, v2
	v_mov_b32_e32 v31, v2
	v_mov_b32_e32 v32, v2
	v_mov_b32_e32 v33, v2
	v_mov_b32_e32 v34, v2
	v_mov_b32_e32 v35, v2
	v_mov_b32_e32 v36, v2
	v_mov_b32_e32 v37, v2
	v_mov_b32_e32 v38, v2
	v_mov_b32_e32 v39, v2
	v_mov_b32_e32 v40, v2
	v_mov_b32_e32 v41, v2
	v_mov_b32_e32 v42, v2
	v_mov_b32_e32 v43, v2
	v_mov_b32_e32 v44, v2
	v_mov_b32_e32 v45, v2
	v_mov_b32_e32 v46, v2
	v_mov_b32_e32 v47, v2
	v_mov_b32_e32 v48, v2
	v_mov_b32_e32 v49, v2
	v_mov_b32_e32 v50, v2
	v_mov_b32_e32 v51, v2
	v_mov_b32_e32 v52, v2
	v_mov_b32_e32 v53, v2
	v_mov_b32_e32 v54, v2
	v_mov_b32_e32 v55, v2
	v_mov_b32_e32 v56, v2
	v_mov_b32_e32 v57, v2
	v_mov_b32_e32 v58, v2
	v_mov_b32_e32 v59, v2
	v_mov_b32_e32 v60, v2
	v_mov_b32_e32 v61, v2
	v_mov_b32_e32 v62, v2
	v_mov_b32_e32 v63, v2
	v_mov_b32_e32 v64, v2
	v_mov_b32_e32 v65, v2
	v_mov_b32_e32 v66, v2
	v_mov_b32_e32 v67, v2
	v_mov_b32_e32 v68, v2
	v_mov_b32_e32 v69, v2
	v_mov_b32_e32 v70, v2
	v_mov_b32_e32 v71, v2
	v_mov_b32_e32 v72, v2
	v_mov_b32_e32 v73, v2
	v_mov_b32_e32 v74, v2
	v_mov_b32_e32 v75, v2
	v_mov_b32_e32 v76, v2
	v_mov_b32_e32 v77, v2
	v_mov_b32_e32 v78, v2
	v_mov_b32_e32 v79, v2
	v_mov_b32_e32 v80, v2
	v_mov_b32_e32 v81, v2
	v_mov_b32_e32 v82, v2
	v_mov_b32_e32 v83, v2
	v_mov_b32_e32 v84, v2
	v_mov_b32_e32 v85, v2
	v_mov_b32_e32 v86, v2
	v_mov_b32_e32 v87, v2
	v_mov_b32_e32 v88, v2
	v_mov_b32_e32 v89, v2
	v_mov_b32_e32 v90, v2
	v_mov_b32_e32 v91, v2
	v_mov_b32_e32 v92, v2
	v_mov_b32_e32 v93, v2
	v_mov_b32_e32 v94, v2
	v_mov_b32_e32 v95, v2
	v_mov_b32_e32 v96, v2
	v_mov_b32_e32 v97, v2
	v_mov_b32_e32 v98, v2
	v_mov_b32_e32 v99, v2
	v_mov_b32_e32 v100, v2
	v_mov_b32_e32 v101, v2
	v_mov_b32_e32 v102, v2
	v_mov_b32_e32 v103, v2
	v_mov_b32_e32 v104, v2
	v_mov_b32_e32 v105, v2
	v_mov_b32_e32 v106, v2
	v_mov_b32_e32 v107, v2
	v_mov_b32_e32 v108, v2
	v_mov_b32_e32 v109, v2
	v_mov_b32_e32 v110, v2
	v_mov_b32_e32 v111, v2
	v_mov_b32_e32 v112, v2
	v_mov_b32_e32 v113, v2
	v_mov_b32_e32 v114, v2
	v_mov_b32_e32 v115, v2
	v_mov_b32_e32 v116, v2
	v_mov_b32_e32 v117, v2
	v_mov_b32_e32 v118, v2
	v_mov_b32_e32 v119, v2
	v_mov_b32_e32 v120, v2
	v_mov_b32_e32 v121, v2
	v_mov_b32_e32 v122, v2
	v_mov_b32_e32 v123, v2
	v_mov_b32_e32 v124, v2
	v_mov_b32_e32 v125, v2
	v_mov_b32_e32 v126, v2
	v_mov_b32_e32 v127, v2
	v_mov_b32_e32 v128, v2
	v_mov_b32_e32 v129, v2
	v_readlane_b32 vcc_lo, v245, 30
	s_nop 0
	s_cmpk_lt_u32 vcc_lo, 0x1000
	s_cbranch_scc1 .Lgp_202

; #define WAIT_V(n) asm volatile("s_waitcnt vmcnt(" #n ")" ::: "memory")
; #define BAR __builtin_amdgcn_s_barrier()
;     ...
;     STAGE(SB(0, 0), Bt, bcol, 0); STAGE(SA(0, 0), A, brow, 0);
;     STAGE(SB(0, 1), Bt, bcol + HALF, 0); STAGE(SA(0, 1), A, brow + HALF, 0);
;     if (wr == 1) BAR;
;     WAIT_V(4); BAR;
;     STAGE(SB(1, 0), Bt, bcol, 1); STAGE(SA(1, 0), A, brow, 1); STAGE(SB(1, 1), Bt, bcol + HALF, 1);
;     WAIT_V(6); BAR;
;     for (int t = 0; t < nt - 2; t += 2) {
.LBB0_417:
	s_add_u32 s34, s8, 0x80
	s_addc_u32 s35, s9, 0
	s_add_i32 s8, s15, 0x18000
	v_mov_b32_e32 v141, v1
	s_waitcnt vmcnt(4)
	s_barrier
	s_mov_b32 m0, s8
	v_lshl_add_u64 v[4:5], s[34:35], 0, v[0:1]
	s_add_i32 s9, s15, 0x1a000
	global_load_lds_dwordx4 v[4:5], off
	v_lshl_add_u64 v[4:5], s[34:35], 0, v[140:141]
	s_add_u32 s34, s18, 0x80
	s_mov_b32 m0, s9
	s_addc_u32 s35, s19, 0
	s_add_i32 s18, s15, 0x8000
	global_load_lds_dwordx4 v[4:5], off
	s_mov_b32 m0, s18
	v_lshl_add_u64 v[4:5], s[34:35], 0, v[0:1]
	s_add_i32 s19, s15, 0xa000
	global_load_lds_dwordx4 v[4:5], off
	v_lshl_add_u64 v[4:5], s[34:35], 0, v[140:141]
	s_add_u32 s34, s20, 0x80
	s_mov_b32 m0, s19
	s_addc_u32 s35, s21, 0
	s_add_i32 s20, s15, 0x1c000
	global_load_lds_dwordx4 v[4:5], off
	s_mov_b32 m0, s20
	v_lshl_add_u64 v[4:5], s[34:35], 0, v[0:1]
	s_add_i32 s21, s15, 0x1e000
	global_load_lds_dwordx4 v[4:5], off
	v_lshl_add_u64 v[4:5], s[34:35], 0, v[140:141]
	s_mov_b32 m0, s21
	v_and_b32_e32 v3, 15, v2
	global_load_lds_dwordx4 v[4:5], off
	v_and_b32_e32 v6, 48, v2
	v_lshlrev_b32_e32 v2, 2, v2
	v_lshlrev_b32_e32 v4, 6, v3
	v_and_b32_e32 v2, 32, v2
	v_bitop3_b32 v142, v4, v2, v6 bitop3:0x36
	v_or_b32_e32 v2, s33, v3
	v_lshlrev_b32_e32 v4, 6, v2
	v_lshlrev_b32_e32 v2, 2, v2
	v_and_b32_e32 v4, 0x3c0, v4
	v_and_b32_e32 v2, 32, v2
	v_readlane_b32 s34, v245, 36
	v_bitop3_b32 v4, v4, v2, v6 bitop3:0x36
	s_lshl_b32 s30, s30, 11
	v_or_b32_e32 v2, s34, v3
	v_lshlrev_b32_e32 v5, 6, v2
	v_lshlrev_b32_e32 v2, 2, v2
	v_and_b32_e32 v5, 0x3c0, v5
	v_and_b32_e32 v2, 32, v2
	v_readlane_b32 s34, v245, 37
	v_bitop3_b32 v5, v5, v2, v6 bitop3:0x36
	s_lshl_b32 s31, s31, 8
	v_or_b32_e32 v2, s34, v3
	v_lshlrev_b32_e32 v7, 6, v2
	v_lshlrev_b32_e32 v2, 2, v2
	s_add_i32 s30, s30, s31
	v_and_b32_e32 v7, 0x3c0, v7
	v_and_b32_e32 v2, 32, v2
	s_ashr_i32 s31, s30, 31
	v_bitop3_b32 v7, v7, v2, v6 bitop3:0x36
	v_or_b32_e32 v2, s85, v3
	s_lshl_b64 s[30:31], s[30:31], 12
	v_readlane_b32 s37, v244, 19
	v_lshlrev_b32_e32 v3, 6, v2
	v_lshlrev_b32_e32 v2, 2, v2
	s_add_u32 s30, s74, s30
	v_add_u32_e32 v133, s37, v4
	v_readlane_b32 s37, v244, 20
	s_waitcnt vmcnt(6)
	v_and_b32_e32 v3, 0x3c0, v3
	v_and_b32_e32 v2, 32, v2
	s_addc_u32 s31, s75, s31
	v_add_u32_e32 v134, s37, v5
	v_readlane_b32 s37, v244, 21
	v_bitop3_b32 v3, v3, v2, v6 bitop3:0x36
	s_add_u32 s34, s38, s6
	v_mov_b32_e32 v2, 0
	v_add_u32_e32 v137, s37, v7
	v_readlane_b32 s37, v244, 22
	s_addc_u32 s35, s39, s7
	s_mov_b32 s36, -2
	s_mov_b64 s[6:7], 0
	v_add_u32_e32 v139, s37, v3
	v_mov_b32_e32 v3, v2
	v_mov_b32_e32 v4, v2
	v_mov_b32_e32 v5, v2
	v_mov_b32_e32 v6, v2
	v_mov_b32_e32 v7, v2
	v_mov_b32_e32 v8, v2
	v_mov_b32_e32 v9, v2
	v_mov_b32_e32 v10, v2
	v_mov_b32_e32 v11, v2
	v_mov_b32_e32 v12, v2
	v_mov_b32_e32 v13, v2
	v_mov_b32_e32 v14, v2
	v_mov_b32_e32 v15, v2
	v_mov_b32_e32 v16, v2
	v_mov_b32_e32 v17, v2
	v_mov_b32_e32 v18, v2
	v_mov_b32_e32 v19, v2
	v_mov_b32_e32 v20, v2
	v_mov_b32_e32 v21, v2
	v_mov_b32_e32 v22, v2
	v_mov_b32_e32 v23, v2
	v_mov_b32_e32 v24, v2
	v_mov_b32_e32 v25, v2
	v_mov_b32_e32 v26, v2
	v_mov_b32_e32 v27, v2
	v_mov_b32_e32 v28, v2
	v_mov_b32_e32 v29, v2
	v_mov_b32_e32 v30, v2
	v_mov_b32_e32 v31, v2
	v_mov_b32_e32 v32, v2
	v_mov_b32_e32 v33, v2
	v_mov_b32_e32 v34, v2
	v_mov_b32_e32 v35, v2
	v_mov_b32_e32 v36, v2
	v_mov_b32_e32 v37, v2
	v_mov_b32_e32 v38, v2
	v_mov_b32_e32 v39, v2
	v_mov_b32_e32 v40, v2
	v_mov_b32_e32 v41, v2
	v_mov_b32_e32 v42, v2
	v_mov_b32_e32 v43, v2
	v_mov_b32_e32 v44, v2
	v_mov_b32_e32 v45, v2
	v_mov_b32_e32 v46, v2
	v_mov_b32_e32 v47, v2
	v_mov_b32_e32 v48, v2
	v_mov_b32_e32 v49, v2
	v_mov_b32_e32 v50, v2
	v_mov_b32_e32 v51, v2
	v_mov_b32_e32 v52, v2
	v_mov_b32_e32 v53, v2
	v_mov_b32_e32 v54, v2
	v_mov_b32_e32 v55, v2
	v_mov_b32_e32 v56, v2
	v_mov_b32_e32 v57, v2
	v_mov_b32_e32 v58, v2
	v_mov_b32_e32 v59, v2
	v_mov_b32_e32 v60, v2
	v_mov_b32_e32 v61, v2
	v_mov_b32_e32 v62, v2
	v_mov_b32_e32 v63, v2
	v_mov_b32_e32 v64, v2
	v_mov_b32_e32 v65, v2
	v_mov_b32_e32 v66, v2
	v_mov_b32_e32 v67, v2
	v_mov_b32_e32 v68, v2
	v_mov_b32_e32 v69, v2
	v_mov_b32_e32 v70, v2
	v_mov_b32_e32 v71, v2
	v_mov_b32_e32 v72, v2
	v_mov_b32_e32 v73, v2
	v_mov_b32_e32 v74, v2
	v_mov_b32_e32 v75, v2
	v_mov_b32_e32 v76, v2
	v_mov_b32_e32 v77, v2
	v_mov_b32_e32 v78, v2
	v_mov_b32_e32 v79, v2
	v_mov_b32_e32 v80, v2
	v_mov_b32_e32 v81, v2
	v_mov_b32_e32 v82, v2
	v_mov_b32_e32 v83, v2
	v_mov_b32_e32 v84, v2
	v_mov_b32_e32 v85, v2
	v_mov_b32_e32 v86, v2
	v_mov_b32_e32 v87, v2
	v_mov_b32_e32 v88, v2
	v_mov_b32_e32 v89, v2
	v_mov_b32_e32 v90, v2
	v_mov_b32_e32 v91, v2
	v_mov_b32_e32 v92, v2
	v_mov_b32_e32 v93, v2
	v_mov_b32_e32 v94, v2
	v_mov_b32_e32 v95, v2
	v_mov_b32_e32 v96, v2
	v_mov_b32_e32 v97, v2
	v_mov_b32_e32 v98, v2
	v_mov_b32_e32 v99, v2
	v_mov_b32_e32 v100, v2
	v_mov_b32_e32 v101, v2
	v_mov_b32_e32 v102, v2
	v_mov_b32_e32 v103, v2
	v_mov_b32_e32 v104, v2
	v_mov_b32_e32 v105, v2
	v_mov_b32_e32 v106, v2
	v_mov_b32_e32 v107, v2
	v_mov_b32_e32 v108, v2
	v_mov_b32_e32 v109, v2
	v_mov_b32_e32 v110, v2
	v_mov_b32_e32 v111, v2
	v_mov_b32_e32 v112, v2
	v_mov_b32_e32 v113, v2
	v_mov_b32_e32 v114, v2
	v_mov_b32_e32 v115, v2
	v_mov_b32_e32 v116, v2
	v_mov_b32_e32 v117, v2
	v_mov_b32_e32 v118, v2
	v_mov_b32_e32 v119, v2
	v_mov_b32_e32 v120, v2
	v_mov_b32_e32 v121, v2
	v_mov_b32_e32 v122, v2
	v_mov_b32_e32 v123, v2
	v_mov_b32_e32 v124, v2
	v_mov_b32_e32 v125, v2
	v_mov_b32_e32 v126, v2
	v_mov_b32_e32 v127, v2
	v_mov_b32_e32 v128, v2
	v_mov_b32_e32 v129, v2
	v_readlane_b32 vcc_lo, v245, 30
	s_nop 0
	s_cmpk_lt_u32 vcc_lo, 0x1000
	s_cbranch_scc1 .Lgp_418
